# branch/out/PEER-query GEMM phases: co-resident block start stagger (s_sleep) removed
# speedup vs baseline: 1.0165x; 1.0018x over previous
.LBB0_698:
	s_or_b64 exec, exec, s[0:1]
	v_readlane_b32 s0, v246, 26
	v_readlane_b32 s1, v246, 27
	s_andn2_b64 vcc, exec, s[0:1]
	s_waitcnt lgkmcnt(0)
	v_cndmask_b32_e64 v0, 0, 1, s[0:1]
	v_cmp_ne_u32_e64 s[6:7], 1, v0
	s_barrier
	s_cbranch_vccnz .LBB0_700
	s_nop 0

.LBB0_763:
	s_or_b64 exec, exec, s[2:3]
	s_and_b64 vcc, exec, s[6:7]
	s_waitcnt lgkmcnt(0)
	s_barrier
	s_cbranch_vccnz .LBB0_765
	s_nop 0

.LBB0_881:
	s_or_b64 exec, exec, s[0:1]
	s_and_b64 vcc, exec, s[6:7]
	s_waitcnt lgkmcnt(0)
	s_barrier
	s_cbranch_vccnz .LBB0_883
	s_nop 0
